# v12 + residual GEMM: last K-loop iteration touches the residual-stream lines the epilogue will load
# baseline (speedup 1.0000x reference)
; #define PG8_STAGE(bufoff, gbase, voff) do { _Pragma("unroll") for (int _i = 0; _i < 2; ++_i) \
;         __builtin_amdgcn_global_load_lds((const unsigned*)((const char*)(gbase) + (voff)[_i]), (PG8_LAS unsigned*)(lds + (bufoff) + ldsw + _i * 8192), 16, 0, 0); } while (0)
; #define PG8_LDA(dst, b, h) do { _Pragma("unroll") for (int m = 0; m < 4; ++m) _Pragma("unroll") for (int k = 0; k < 2; ++k) dst[m][k] = *(const PG8_LAS bf16x8*)(lds + PG8_SA(b, h) + aoff + m * 2048 + k * 1024); } while (0)
; #define PG8_LDB(dst, b, h) do { _Pragma("unroll") for (int n = 0; n < 2; ++n) _Pragma("unroll") for (int k = 0; k < 2; ++k) dst[n][k] = *(const PG8_LAS bf16x8*)(lds + PG8_SB(b, h) + boff + n * 2048 + k * 1024); } while (0)
; #define PG8_MMA(ai, bj, At, Bt) do { __builtin_amdgcn_s_setprio(1); _Pragma("unroll") for (int m = 0; m < 4; ++m) _Pragma("unroll") for (int n = 0; n < 2; ++n) _Pragma("unroll") for (int k = 0; k < 2; ++k) \
;         acc[ai][bj][m][n] = __builtin_amdgcn_mfma_f32_16x16x32_bf16(Bt[n][k], At[m][k], acc[ai][bj][m][n], 0, 0, 0); __builtin_amdgcn_s_setprio(0); } while (0)
; #define PG8_WAIT_V(n) asm volatile("s_waitcnt vmcnt(" #n ")" ::: "memory")
; #define PG8_WAIT_L(n) asm volatile("s_waitcnt lgkmcnt(" #n ")" ::: "memory")
; #define PG8_BAR __builtin_amdgcn_s_barrier()
; #define PG8_SCHED __builtin_amdgcn_sched_barrier(0)
; template <class Epi, class Sched, bool ALIGN_EPI = false, bool SP2 = false>
; __device__ __forceinline__ void gemm_phase(PG8_LAS unsigned char* lds, const Gemm g, const Sched& S, const Epi& E, const int tid) {
;     ...
;         for (int t = 0; t < nt; t += 2) {
;             const bool last = (t == nt - 2);
;             const char* a1 = cA + (size_t)(t + 1) * kstep;
;             const char* a2 = last ? nA : cA + (size_t)(t + 2) * kstep; const char* b2 = last ? nB : cB + (size_t)(t + 2) * kstep;
;             const char* a3 = a2 + kstep; const char* b3 = b2 + kstep;
;             if (last && has_next) S.a_ready(nxt);
;             if constexpr (SP2) {
;             PG8_LDB(B0, 0, 0); PG8_LDB(B1, 0, 1); PG8_SCHED; PG8_LDA(At, 0, 0); PG8_STAGE(PG8_SA(1, 1), a1 + hstep, voffA);
;             PG8_WAIT_V(8); PG8_WAIT_L(0); PG8_BAR; PG8_MMA(0, 0, At, B0); PG8_MMA(0, 1, At, B1); PG8_BAR; PG8_SCHED;
.LBB0_881:
	s_add_i32 s59, s34, 2
	s_add_u32 s60, s30, 0x80
	s_addc_u32 s35, s31, 0
	s_add_i32 s62, 0, 0x10000
	s_cmp_eq_u32 s52, s34
	s_cbranch_scc0 .Lres_touch_skip
	v_lshl_add_u32 v218, s55, 8, v223
	v_lshl_or_b32 v206, s56, 8, v225
	v_mov_b32_e32 v219, 0
	v_mov_b32_e32 v207, 0
	v_lshlrev_b64 v[218:219], 11, v[218:219]
	v_lshlrev_b32_e32 v206, 1, v206
	v_lshl_add_u64 v[218:219], v[218:219], 0, v[206:207]
	v_lshl_add_u64 v[218:219], s[24:25], 0, v[218:219]
	s_mov_b64 s[74:75], 0x8000
	global_load_dword v209, v[218:219], off
	global_load_dword v209, v[218:219], off offset:256
	v_lshl_add_u64 v[218:219], v[218:219], 0, s[74:75]
	global_load_dword v209, v[218:219], off
	global_load_dword v209, v[218:219], off offset:256
	v_lshl_add_u64 v[218:219], v[218:219], 0, s[74:75]
	global_load_dword v209, v[218:219], off
	global_load_dword v209, v[218:219], off offset:256
	v_lshl_add_u64 v[218:219], v[218:219], 0, s[74:75]
	global_load_dword v209, v[218:219], off
	global_load_dword v209, v[218:219], off offset:256
	s_mov_b64 s[76:77], 0x28000
	v_lshl_add_u64 v[218:219], v[218:219], 0, s[76:77]
	global_load_dword v209, v[218:219], off
	global_load_dword v209, v[218:219], off offset:256
	v_lshl_add_u64 v[218:219], v[218:219], 0, s[74:75]
	global_load_dword v209, v[218:219], off
	global_load_dword v209, v[218:219], off offset:256
	v_lshl_add_u64 v[218:219], v[218:219], 0, s[74:75]
	global_load_dword v209, v[218:219], off
	global_load_dword v209, v[218:219], off offset:256
	v_lshl_add_u64 v[218:219], v[218:219], 0, s[74:75]
	global_load_dword v209, v[218:219], off
	global_load_dword v209, v[218:219], off offset:256
.Lres_touch_skip:
	s_cmp_eq_u32 s52, s34
	s_cselect_b32 s35, s3, s35
	s_cselect_b32 s34, s2, s60
	v_add_u32_e32 v138, s62, v224
	s_cselect_b32 s61, s5, s58
	s_cselect_b32 s60, s4, s57
	s_add_i32 s63, 0, 0x14000
	ds_read_b128 v[154:157], v138
	ds_read_b128 v[158:161], v138 offset:1024
	ds_read_b128 v[162:165], v138 offset:2048
	ds_read_b128 v[166:169], v138 offset:3072
	v_add_u32_e32 v138, s63, v224
	ds_read_b128 v[170:173], v138
	ds_read_b128 v[174:177], v138 offset:1024
	ds_read_b128 v[178:181], v138 offset:2048
	ds_read_b128 v[182:185], v138 offset:3072
	v_lshl_add_u64 v[138:139], s[30:31], 0, v[134:135]
	s_add_i32 m0, s42, 0xc000
	ds_read_b128 v[186:189], v226
	ds_read_b128 v[190:193], v226 offset:1024
	ds_read_b128 v[194:197], v226 offset:2048
	ds_read_b128 v[198:201], v226 offset:3072
	ds_read_b128 v[202:205], v226 offset:4096
	ds_read_b128 v[228:231], v226 offset:5120
	ds_read_b128 v[232:235], v226 offset:6144
	ds_read_b128 v[236:239], v226 offset:7168
	global_load_lds_dwordx4 v[138:139], off
	v_lshl_add_u64 v[138:139], s[30:31], 0, v[136:137]
	s_add_i32 m0, s42, 0xe000
	s_nop 0
	global_load_lds_dwordx4 v[138:139], off
	s_waitcnt vmcnt(8)
	s_waitcnt lgkmcnt(0)
	s_barrier
	s_setprio 1
	s_waitcnt lgkmcnt(0)
	v_mfma_f32_16x16x32_bf16 v[124:127], v[154:157], v[186:189], v[124:127]
	v_mfma_f32_16x16x32_bf16 v[120:123], v[162:165], v[186:189], v[120:123]
	v_mfma_f32_16x16x32_bf16 v[116:119], v[154:157], v[194:197], v[116:119]
	v_mfma_f32_16x16x32_bf16 v[112:115], v[162:165], v[194:197], v[112:115]
	v_mfma_f32_16x16x32_bf16 v[108:111], v[154:157], v[202:205], v[108:111]
	v_mfma_f32_16x16x32_bf16 v[104:107], v[162:165], v[202:205], v[104:107]
	v_mfma_f32_16x16x32_bf16 v[100:103], v[154:157], v[232:235], v[100:103]
	v_mfma_f32_16x16x32_bf16 v[96:99], v[162:165], v[232:235], v[96:99]
	v_mfma_f32_16x16x32_bf16 v[124:127], v[158:161], v[190:193], v[124:127]
	v_mfma_f32_16x16x32_bf16 v[120:123], v[166:169], v[190:193], v[120:123]
	v_mfma_f32_16x16x32_bf16 v[116:119], v[158:161], v[198:201], v[116:119]
	v_mfma_f32_16x16x32_bf16 v[112:115], v[166:169], v[198:201], v[112:115]
	v_mfma_f32_16x16x32_bf16 v[108:111], v[158:161], v[228:231], v[108:111]
	v_mfma_f32_16x16x32_bf16 v[104:107], v[166:169], v[228:231], v[104:107]
	v_mfma_f32_16x16x32_bf16 v[100:103], v[158:161], v[236:239], v[100:103]
	v_mfma_f32_16x16x32_bf16 v[96:99], v[166:169], v[236:239], v[96:99]
	s_setprio 0
	s_setprio 1
	v_mfma_f32_16x16x32_bf16 v[60:63], v[170:173], v[186:189], v[60:63]
	v_mfma_f32_16x16x32_bf16 v[56:59], v[178:181], v[186:189], v[56:59]
	v_mfma_f32_16x16x32_bf16 v[52:55], v[170:173], v[194:197], v[52:55]
	v_mfma_f32_16x16x32_bf16 v[48:51], v[178:181], v[194:197], v[48:51]
	v_mfma_f32_16x16x32_bf16 v[44:47], v[170:173], v[202:205], v[44:47]
	v_mfma_f32_16x16x32_bf16 v[40:43], v[178:181], v[202:205], v[40:43]
	v_mfma_f32_16x16x32_bf16 v[36:39], v[170:173], v[232:235], v[36:39]
	v_mfma_f32_16x16x32_bf16 v[32:35], v[178:181], v[232:235], v[32:35]
	v_mfma_f32_16x16x32_bf16 v[60:63], v[174:177], v[190:193], v[60:63]
	v_mfma_f32_16x16x32_bf16 v[56:59], v[182:185], v[190:193], v[56:59]
	v_mfma_f32_16x16x32_bf16 v[52:55], v[174:177], v[198:201], v[52:55]
	v_mfma_f32_16x16x32_bf16 v[48:51], v[182:185], v[198:201], v[48:51]
	v_mfma_f32_16x16x32_bf16 v[44:47], v[174:177], v[228:231], v[44:47]
	v_mfma_f32_16x16x32_bf16 v[40:43], v[182:185], v[228:231], v[40:43]
	v_mfma_f32_16x16x32_bf16 v[36:39], v[174:177], v[236:239], v[36:39]
	v_mfma_f32_16x16x32_bf16 v[32:35], v[182:185], v[236:239], v[32:35]
	s_setprio 0
	s_barrier
; #define PG8_STAGE(bufoff, gbase, voff) do { _Pragma("unroll") for (int _i = 0; _i < 2; ++_i) \
;         __builtin_amdgcn_global_load_lds((const unsigned*)((const char*)(gbase) + (voff)[_i]), (PG8_LAS unsigned*)(lds + (bufoff) + ldsw + _i * 8192), 16, 0, 0); } while (0)
; #define PG8_LDA(dst, b, h) do { _Pragma("unroll") for (int m = 0; m < 4; ++m) _Pragma("unroll") for (int k = 0; k < 2; ++k) dst[m][k] = *(const PG8_LAS bf16x8*)(lds + PG8_SA(b, h) + aoff + m * 2048 + k * 1024); } while (0)
; #define PG8_LDB(dst, b, h) do { _Pragma("unroll") for (int n = 0; n < 2; ++n) _Pragma("unroll") for (int k = 0; k < 2; ++k) dst[n][k] = *(const PG8_LAS bf16x8*)(lds + PG8_SB(b, h) + boff + n * 2048 + k * 1024); } while (0)
; #define PG8_MMA(ai, bj, At, Bt) do { __builtin_amdgcn_s_setprio(1); _Pragma("unroll") for (int m = 0; m < 4; ++m) _Pragma("unroll") for (int n = 0; n < 2; ++n) _Pragma("unroll") for (int k = 0; k < 2; ++k) \
;         acc[ai][bj][m][n] = __builtin_amdgcn_mfma_f32_16x16x32_bf16(Bt[n][k], At[m][k], acc[ai][bj][m][n], 0, 0, 0); __builtin_amdgcn_s_setprio(0); } while (0)
; #define PG8_WAIT_V(n) asm volatile("s_waitcnt vmcnt(" #n ")" ::: "memory")
; #define PG8_WAIT_L(n) asm volatile("s_waitcnt lgkmcnt(" #n ")" ::: "memory")
; #define PG8_BAR __builtin_amdgcn_s_barrier()
; #define PG8_SCHED __builtin_amdgcn_sched_barrier(0)
; template <class Epi, class Sched, bool ALIGN_EPI = false, bool SP2 = false>
; __device__ __forceinline__ void gemm_phase(PG8_LAS unsigned char* lds, const Gemm g, const Sched& S, const Epi& E, const int tid) {
;     ...
;             PG8_LDA(At, 0, 1); PG8_STAGE(PG8_SB(0, 0), b2, voffB); PG8_STAGE(PG8_SB(0, 1), b2 + hstep, voffB); PG8_STAGE(PG8_SA(0, 0), a2, voffA);
;             PG8_WAIT_V(8); PG8_WAIT_L(0); PG8_BAR; PG8_MMA(1, 0, At, B0); PG8_MMA(1, 1, At, B1); PG8_BAR; PG8_SCHED;
;             PG8_LDB(B0, 1, 0); PG8_LDB(B1, 1, 1); PG8_SCHED; PG8_LDA(At, 1, 0); PG8_STAGE(PG8_SA(0, 1), a2 + hstep, voffA);
;             PG8_WAIT_V(8); PG8_WAIT_L(0); PG8_BAR; PG8_MMA(0, 0, At, B0); PG8_MMA(0, 1, At, B1); PG8_BAR; PG8_SCHED;
	s_add_i32 s62, s62, s41
	v_lshl_add_u64 v[138:139], s[60:61], 0, v[146:147]
	s_mov_b32 m0, s62
	ds_read_b128 v[186:189], v226 offset:16384
	ds_read_b128 v[190:193], v226 offset:17408
	ds_read_b128 v[194:197], v226 offset:18432
	ds_read_b128 v[198:201], v226 offset:19456
	ds_read_b128 v[202:205], v226 offset:20480
	ds_read_b128 v[228:231], v226 offset:21504
	ds_read_b128 v[232:235], v226 offset:22528
	ds_read_b128 v[236:239], v226 offset:23552
	global_load_lds_dwordx4 v[138:139], off
	s_add_i32 m0, s62, 0x2000
	v_lshl_add_u64 v[142:143], s[60:61], 0, v[132:133]
	s_add_u32 s60, s60, s10
	s_addc_u32 s61, s61, 0
	s_add_i32 s62, s63, s41
	global_load_lds_dwordx4 v[142:143], off
	v_lshl_add_u64 v[240:241], s[60:61], 0, v[146:147]
	s_mov_b32 m0, s62
	v_lshl_add_u64 v[242:243], s[60:61], 0, v[132:133]
	global_load_lds_dwordx4 v[240:241], off
	s_add_i32 m0, s62, 0x2000
	v_lshl_add_u64 v[244:245], s[34:35], 0, v[128:129]
	global_load_lds_dwordx4 v[242:243], off
	s_mov_b32 m0, s42
	v_lshl_add_u64 v[246:247], s[34:35], 0, v[130:131]
	global_load_lds_dwordx4 v[244:245], off
	s_mov_b32 m0, s43
	s_nop 0
	global_load_lds_dwordx4 v[246:247], off
	s_waitcnt vmcnt(8)
	s_waitcnt lgkmcnt(0)
	s_barrier
	s_setprio 1
	s_waitcnt lgkmcnt(0)
	v_mfma_f32_16x16x32_bf16 v[92:95], v[154:157], v[186:189], v[92:95]
	v_mfma_f32_16x16x32_bf16 v[88:91], v[162:165], v[186:189], v[88:91]
	v_mfma_f32_16x16x32_bf16 v[84:87], v[154:157], v[194:197], v[84:87]
	v_mfma_f32_16x16x32_bf16 v[80:83], v[162:165], v[194:197], v[80:83]
	v_mfma_f32_16x16x32_bf16 v[76:79], v[154:157], v[202:205], v[76:79]
	v_mfma_f32_16x16x32_bf16 v[72:75], v[162:165], v[202:205], v[72:75]
	v_mfma_f32_16x16x32_bf16 v[68:71], v[154:157], v[232:235], v[68:71]
	v_mfma_f32_16x16x32_bf16 v[64:67], v[162:165], v[232:235], v[64:67]
	v_mfma_f32_16x16x32_bf16 v[92:95], v[158:161], v[190:193], v[92:95]
	v_mfma_f32_16x16x32_bf16 v[88:91], v[166:169], v[190:193], v[88:91]
	v_mfma_f32_16x16x32_bf16 v[84:87], v[158:161], v[198:201], v[84:87]
	v_mfma_f32_16x16x32_bf16 v[80:83], v[166:169], v[198:201], v[80:83]
	v_mfma_f32_16x16x32_bf16 v[76:79], v[158:161], v[228:231], v[76:79]
	v_mfma_f32_16x16x32_bf16 v[72:75], v[166:169], v[228:231], v[72:75]
	v_mfma_f32_16x16x32_bf16 v[68:71], v[158:161], v[236:239], v[68:71]
	v_mfma_f32_16x16x32_bf16 v[64:67], v[166:169], v[236:239], v[64:67]
	s_setprio 0
	s_setprio 1
	v_mfma_f32_16x16x32_bf16 v[28:31], v[170:173], v[186:189], v[28:31]
	v_mfma_f32_16x16x32_bf16 v[24:27], v[178:181], v[186:189], v[24:27]
	v_mfma_f32_16x16x32_bf16 v[20:23], v[170:173], v[194:197], v[20:23]
	v_mfma_f32_16x16x32_bf16 v[16:19], v[178:181], v[194:197], v[16:19]
	v_mfma_f32_16x16x32_bf16 v[12:15], v[170:173], v[202:205], v[12:15]
	v_mfma_f32_16x16x32_bf16 v[8:11], v[178:181], v[202:205], v[8:11]
	v_mfma_f32_16x16x32_bf16 v[4:7], v[170:173], v[232:235], v[4:7]
	v_mfma_f32_16x16x32_bf16 v[0:3], v[178:181], v[232:235], v[0:3]
	v_mfma_f32_16x16x32_bf16 v[28:31], v[174:177], v[190:193], v[28:31]
	v_mfma_f32_16x16x32_bf16 v[24:27], v[182:185], v[190:193], v[24:27]
	v_mfma_f32_16x16x32_bf16 v[20:23], v[174:177], v[198:201], v[20:23]
	v_mfma_f32_16x16x32_bf16 v[16:19], v[182:185], v[198:201], v[16:19]
	v_mfma_f32_16x16x32_bf16 v[12:15], v[174:177], v[228:231], v[12:15]
	v_mfma_f32_16x16x32_bf16 v[8:11], v[182:185], v[228:231], v[8:11]
	v_mfma_f32_16x16x32_bf16 v[4:7], v[174:177], v[236:239], v[4:7]
	v_mfma_f32_16x16x32_bf16 v[0:3], v[182:185], v[236:239], v[0:3]
	s_setprio 0
	s_barrier
	s_add_i32 s60, 0, 0x18000
	v_add_u32_e32 v140, s60, v224
	s_add_i32 s61, 0, 0x1c000
	ds_read_b128 v[154:157], v140
	ds_read_b128 v[158:161], v140 offset:1024
	ds_read_b128 v[162:165], v140 offset:2048
	ds_read_b128 v[166:169], v140 offset:3072
	v_add_u32_e32 v140, s61, v224
	ds_read_b128 v[170:173], v140
	ds_read_b128 v[174:177], v140 offset:1024
	ds_read_b128 v[178:181], v140 offset:2048
	ds_read_b128 v[182:185], v140 offset:3072
	s_add_u32 s34, s34, s10
	s_addc_u32 s35, s35, 0
	s_mov_b32 m0, s44
	v_lshl_add_u64 v[248:249], s[34:35], 0, v[128:129]
	ds_read_b128 v[186:189], v226 offset:32768
	ds_read_b128 v[190:193], v226 offset:33792
	ds_read_b128 v[194:197], v226 offset:34816
	ds_read_b128 v[198:201], v226 offset:35840
	ds_read_b128 v[202:205], v226 offset:36864
	ds_read_b128 v[228:231], v226 offset:37888
	ds_read_b128 v[232:235], v226 offset:38912
	ds_read_b128 v[236:239], v226 offset:39936
	global_load_lds_dwordx4 v[248:249], off
	v_lshl_add_u64 v[248:249], s[34:35], 0, v[130:131]
	s_mov_b32 m0, s45
	s_nop 0
	global_load_lds_dwordx4 v[248:249], off
	s_waitcnt vmcnt(8)
	s_waitcnt lgkmcnt(0)
	s_barrier
; #define PG8_STAGE(bufoff, gbase, voff) do { _Pragma("unroll") for (int _i = 0; _i < 2; ++_i) \
;         __builtin_amdgcn_global_load_lds((const unsigned*)((const char*)(gbase) + (voff)[_i]), (PG8_LAS unsigned*)(lds + (bufoff) + ldsw + _i * 8192), 16, 0, 0); } while (0)
; #define PG8_LDA(dst, b, h) do { _Pragma("unroll") for (int m = 0; m < 4; ++m) _Pragma("unroll") for (int k = 0; k < 2; ++k) dst[m][k] = *(const PG8_LAS bf16x8*)(lds + PG8_SA(b, h) + aoff + m * 2048 + k * 1024); } while (0)
; #define PG8_MMA(ai, bj, At, Bt) do { __builtin_amdgcn_s_setprio(1); _Pragma("unroll") for (int m = 0; m < 4; ++m) _Pragma("unroll") for (int n = 0; n < 2; ++n) _Pragma("unroll") for (int k = 0; k < 2; ++k) \
;         acc[ai][bj][m][n] = __builtin_amdgcn_mfma_f32_16x16x32_bf16(Bt[n][k], At[m][k], acc[ai][bj][m][n], 0, 0, 0); __builtin_amdgcn_s_setprio(0); } while (0)
; #define PG8_WAIT_V(n) asm volatile("s_waitcnt vmcnt(" #n ")" ::: "memory")
; #define PG8_WAIT_L(n) asm volatile("s_waitcnt lgkmcnt(" #n ")" ::: "memory")
; #define PG8_BAR __builtin_amdgcn_s_barrier()
; #define PG8_SCHED __builtin_amdgcn_sched_barrier(0)
; template <class Epi, class Sched, bool ALIGN_EPI = false, bool SP2 = false>
; __device__ __forceinline__ void gemm_phase(PG8_LAS unsigned char* lds, const Gemm g, const Sched& S, const Epi& E, const int tid) {
;     ...
;         for (int t = 0; t < nt; t += 2) {
;     ...
;             PG8_WAIT_V(8); PG8_WAIT_L(0); PG8_BAR; PG8_MMA(0, 0, At, B0); PG8_MMA(0, 1, At, B1); PG8_BAR; PG8_SCHED;
;             PG8_LDA(At, 1, 1); PG8_STAGE(PG8_SB(1, 0), b3, voffB); PG8_STAGE(PG8_SB(1, 1), b3 + hstep, voffB); PG8_STAGE(PG8_SA(1, 0), a3, voffA);
;             PG8_WAIT_V(8); PG8_WAIT_L(0); PG8_BAR; PG8_MMA(1, 0, At, B0); PG8_MMA(1, 1, At, B1); PG8_BAR; PG8_SCHED;
	s_setprio 1
	s_waitcnt lgkmcnt(0)
	v_mfma_f32_16x16x32_bf16 v[124:127], v[154:157], v[186:189], v[124:127]
	v_mfma_f32_16x16x32_bf16 v[120:123], v[162:165], v[186:189], v[120:123]
	v_mfma_f32_16x16x32_bf16 v[116:119], v[154:157], v[194:197], v[116:119]
	v_mfma_f32_16x16x32_bf16 v[112:115], v[162:165], v[194:197], v[112:115]
	v_mfma_f32_16x16x32_bf16 v[108:111], v[154:157], v[202:205], v[108:111]
	v_mfma_f32_16x16x32_bf16 v[104:107], v[162:165], v[202:205], v[104:107]
	v_mfma_f32_16x16x32_bf16 v[100:103], v[154:157], v[232:235], v[100:103]
	v_mfma_f32_16x16x32_bf16 v[96:99], v[162:165], v[232:235], v[96:99]
	v_mfma_f32_16x16x32_bf16 v[124:127], v[158:161], v[190:193], v[124:127]
	v_mfma_f32_16x16x32_bf16 v[120:123], v[166:169], v[190:193], v[120:123]
	v_mfma_f32_16x16x32_bf16 v[116:119], v[158:161], v[198:201], v[116:119]
	v_mfma_f32_16x16x32_bf16 v[112:115], v[166:169], v[198:201], v[112:115]
	v_mfma_f32_16x16x32_bf16 v[108:111], v[158:161], v[228:231], v[108:111]
	v_mfma_f32_16x16x32_bf16 v[104:107], v[166:169], v[228:231], v[104:107]
	v_mfma_f32_16x16x32_bf16 v[100:103], v[158:161], v[236:239], v[100:103]
	v_mfma_f32_16x16x32_bf16 v[96:99], v[166:169], v[236:239], v[96:99]
	s_setprio 0
	s_setprio 1
	v_mfma_f32_16x16x32_bf16 v[60:63], v[170:173], v[186:189], v[60:63]
	v_mfma_f32_16x16x32_bf16 v[56:59], v[178:181], v[186:189], v[56:59]
	v_mfma_f32_16x16x32_bf16 v[52:55], v[170:173], v[194:197], v[52:55]
	v_mfma_f32_16x16x32_bf16 v[48:51], v[178:181], v[194:197], v[48:51]
	v_mfma_f32_16x16x32_bf16 v[44:47], v[170:173], v[202:205], v[44:47]
	v_mfma_f32_16x16x32_bf16 v[40:43], v[178:181], v[202:205], v[40:43]
	v_mfma_f32_16x16x32_bf16 v[36:39], v[170:173], v[232:235], v[36:39]
	v_mfma_f32_16x16x32_bf16 v[32:35], v[178:181], v[232:235], v[32:35]
	v_mfma_f32_16x16x32_bf16 v[60:63], v[174:177], v[190:193], v[60:63]
	v_mfma_f32_16x16x32_bf16 v[56:59], v[182:185], v[190:193], v[56:59]
	v_mfma_f32_16x16x32_bf16 v[52:55], v[174:177], v[198:201], v[52:55]
	v_mfma_f32_16x16x32_bf16 v[48:51], v[182:185], v[198:201], v[48:51]
	v_mfma_f32_16x16x32_bf16 v[44:47], v[174:177], v[228:231], v[44:47]
	v_mfma_f32_16x16x32_bf16 v[40:43], v[182:185], v[228:231], v[40:43]
	v_mfma_f32_16x16x32_bf16 v[36:39], v[174:177], v[236:239], v[36:39]
	v_mfma_f32_16x16x32_bf16 v[32:35], v[182:185], v[236:239], v[32:35]
	s_setprio 0
	s_barrier
	s_add_i32 s34, s60, s41
	v_lshl_add_u64 v[138:139], v[138:139], 0, s[68:69]
	s_mov_b32 m0, s34
	ds_read_b128 v[186:189], v226 offset:49152
	ds_read_b128 v[190:193], v226 offset:50176
	ds_read_b128 v[194:197], v226 offset:51200
	ds_read_b128 v[198:201], v226 offset:52224
	ds_read_b128 v[202:205], v226 offset:53248
	ds_read_b128 v[228:231], v226 offset:54272
	ds_read_b128 v[232:235], v226 offset:55296
	ds_read_b128 v[236:239], v226 offset:56320
	global_load_lds_dwordx4 v[138:139], off
	v_lshl_add_u64 v[138:139], v[142:143], 0, s[68:69]
	s_add_i32 m0, s34, 0x2000
	s_add_i32 s34, s61, s41
	global_load_lds_dwordx4 v[138:139], off
	v_lshl_add_u64 v[138:139], v[240:241], 0, s[68:69]
	s_mov_b32 m0, s34
	s_nop 0
	global_load_lds_dwordx4 v[138:139], off
	v_lshl_add_u64 v[138:139], v[242:243], 0, s[68:69]
	s_add_i32 m0, s34, 0x2000
	s_nop 0
	global_load_lds_dwordx4 v[138:139], off
	v_lshl_add_u64 v[138:139], v[244:245], 0, s[68:69]
	s_mov_b32 m0, s48
	s_nop 0
	global_load_lds_dwordx4 v[138:139], off
	v_lshl_add_u64 v[138:139], v[246:247], 0, s[68:69]
	s_mov_b32 m0, s49
	s_nop 0
	global_load_lds_dwordx4 v[138:139], off
	s_waitcnt vmcnt(8)
	s_waitcnt lgkmcnt(0)
	s_barrier
	s_setprio 1
	s_waitcnt lgkmcnt(0)
	v_mfma_f32_16x16x32_bf16 v[92:95], v[154:157], v[186:189], v[92:95]
	v_mfma_f32_16x16x32_bf16 v[88:91], v[162:165], v[186:189], v[88:91]
	v_mfma_f32_16x16x32_bf16 v[84:87], v[154:157], v[194:197], v[84:87]
	v_mfma_f32_16x16x32_bf16 v[80:83], v[162:165], v[194:197], v[80:83]
	v_mfma_f32_16x16x32_bf16 v[76:79], v[154:157], v[202:205], v[76:79]
	v_mfma_f32_16x16x32_bf16 v[72:75], v[162:165], v[202:205], v[72:75]
	v_mfma_f32_16x16x32_bf16 v[68:71], v[154:157], v[232:235], v[68:71]
	v_mfma_f32_16x16x32_bf16 v[64:67], v[162:165], v[232:235], v[64:67]
	v_mfma_f32_16x16x32_bf16 v[92:95], v[158:161], v[190:193], v[92:95]
	v_mfma_f32_16x16x32_bf16 v[88:91], v[166:169], v[190:193], v[88:91]
	v_mfma_f32_16x16x32_bf16 v[84:87], v[158:161], v[198:201], v[84:87]
	v_mfma_f32_16x16x32_bf16 v[80:83], v[166:169], v[198:201], v[80:83]
	v_mfma_f32_16x16x32_bf16 v[76:79], v[158:161], v[228:231], v[76:79]
	v_mfma_f32_16x16x32_bf16 v[72:75], v[166:169], v[228:231], v[72:75]
	v_mfma_f32_16x16x32_bf16 v[68:71], v[158:161], v[236:239], v[68:71]
	v_mfma_f32_16x16x32_bf16 v[64:67], v[166:169], v[236:239], v[64:67]
	s_setprio 0
	s_setprio 1
	v_mfma_f32_16x16x32_bf16 v[28:31], v[170:173], v[186:189], v[28:31]
	v_mfma_f32_16x16x32_bf16 v[24:27], v[178:181], v[186:189], v[24:27]
	v_mfma_f32_16x16x32_bf16 v[20:23], v[170:173], v[194:197], v[20:23]
	v_mfma_f32_16x16x32_bf16 v[16:19], v[178:181], v[194:197], v[16:19]
	v_mfma_f32_16x16x32_bf16 v[12:15], v[170:173], v[202:205], v[12:15]
	v_mfma_f32_16x16x32_bf16 v[8:11], v[178:181], v[202:205], v[8:11]
	v_mfma_f32_16x16x32_bf16 v[4:7], v[170:173], v[232:235], v[4:7]
	v_mfma_f32_16x16x32_bf16 v[0:3], v[178:181], v[232:235], v[0:3]
	v_mfma_f32_16x16x32_bf16 v[28:31], v[174:177], v[190:193], v[28:31]
	v_mfma_f32_16x16x32_bf16 v[24:27], v[182:185], v[190:193], v[24:27]
	v_mfma_f32_16x16x32_bf16 v[20:23], v[174:177], v[198:201], v[20:23]
	v_mfma_f32_16x16x32_bf16 v[16:19], v[182:185], v[198:201], v[16:19]
	v_mfma_f32_16x16x32_bf16 v[12:15], v[174:177], v[228:231], v[12:15]
	v_mfma_f32_16x16x32_bf16 v[8:11], v[182:185], v[228:231], v[8:11]
	v_mfma_f32_16x16x32_bf16 v[4:7], v[174:177], v[236:239], v[4:7]
	v_mfma_f32_16x16x32_bf16 v[0:3], v[182:185], v[236:239], v[0:3]
	s_setprio 0
	s_barrier
	s_add_u32 s30, s30, 0x100
	s_addc_u32 s31, s31, 0
	s_add_u32 s57, s57, 0x100
	s_addc_u32 s58, s58, 0
	s_cmp_ge_u32 s59, s51
	s_mov_b32 s34, s59
	s_cbranch_scc0 .LBB0_881
	s_and_b64 vcc, exec, s[28:29]
	s_cbranch_vccz .LBB0_884
	s_barrier
